# phase-start parameter / flag loads of P4, P5, P10, P11 issued during the preceding grid barrier wait (all waves), original load sites become register copies
# speedup vs baseline: 1.0005x; 1.0005x over previous
.Lgb3_poll:
	s_or_b64 exec, exec, s[0:1]
	v_mov_b32_e32 v32, 0x3308000
	v_mov_b32_e32 v33, 0
	global_load_dwordx2 v[34:35], v32, s[44:45] offset:72
	global_load_dwordx4 v[36:39], v32, s[44:45] offset:136
	global_load_dwordx2 v[40:41], v33, s[6:7]
	s_and_b64 exec, s[0:1], s[10:11]
	v_mov_b32_e32 v1, 0x3323000
	s_mov_b32 s77, 0

.Lgb3_rel:
	buffer_inv sc1
	s_waitcnt vmcnt(0)
	s_branch .LBB0_645
.Lgb3_other:
	s_or_b64 exec, exec, s[0:1]
	v_mov_b32_e32 v32, 0x3308000
	v_mov_b32_e32 v33, 0
	global_load_dwordx2 v[34:35], v32, s[44:45] offset:72
	global_load_dwordx4 v[36:39], v32, s[44:45] offset:136
	global_load_dwordx2 v[40:41], v33, s[6:7]
.LBB0_645:
	s_or_b64 exec, exec, s[0:1]
	v_mov_b32_e32 v7, 0
	s_waitcnt lgkmcnt(0)
	s_barrier
	v_mov_b32_e32 v0, s44
	v_mov_b32_e32 v1, s45
	v_mov_b32_e32 v6, 0x3308000
	s_waitcnt vmcnt(0)
	v_mov_b32_e32 v4, v34
	v_mov_b32_e32 v5, v35
	s_cmpk_gt_i32 s52, 0x7f7
	v_lshrrev_b32_e32 v230, 5, v229
	s_waitcnt vmcnt(1)
	v_readfirstlane_b32 s4, v0
	v_readfirstlane_b32 s5, v1
	s_cbranch_scc1 .LBB0_661
	v_mov_b32_e32 v0, v36
	v_mov_b32_e32 v1, v37
	v_mov_b32_e32 v2, v38
	v_mov_b32_e32 v3, v39
	v_mov_b32_e32 v12, v40
	v_mov_b32_e32 v13, v41
	s_add_u32 s16, s4, 0x3f00000
	s_addc_u32 s21, s5, 0
	v_lshlrev_b32_e32 v6, 2, v229
	s_add_u32 s22, s4, 0x4600000
	v_lshlrev_b32_e32 v8, 9, v230
	v_lshlrev_b32_e32 v9, 3, v229
	s_movk_i32 s14, 0x3d07
	v_lshlrev_b32_e32 v10, 5, v229
	v_mbcnt_hi_u32_b32 v22, -1, v228
	s_addc_u32 s23, s5, 0
	s_mov_b64 s[2:3], 0x3400000
	v_or3_b32 v8, v8, v9, s14
	v_and_b32_e32 v23, 0x700, v10
	v_or_b32_e32 v10, 0x38f8, v10
	v_and_b32_e32 v9, 64, v22
	s_add_u32 s24, s4, 0x4500000
	v_cmp_lt_u32_e64 s[0:1], 31, v229
	s_mov_b64 s[6:7], 0x1000
	s_movk_i32 s17, 0x7fff
	v_mov_b32_e32 v20, 0x358637bd
	s_mov_b32 s20, 0xf800000
	v_mov_b32_e32 v21, 0x260
	s_mov_b64 s[8:9], 0x1f00
	v_xor_b32_e32 v24, 1, v22
	v_xor_b32_e32 v25, 2, v22
	v_lshlrev_b32_e32 v8, 1, v8
	v_lshlrev_b32_e32 v10, 1, v10
	v_add_u32_e32 v26, 64, v9
	s_addc_u32 s25, s5, 0
	s_mul_i32 s26, s52, 6
	s_add_i32 s86, s26, 6
	s_waitcnt vmcnt(1)
	v_lshl_add_u64 v[0:1], v[0:1], 0, v[6:7]
	s_waitcnt vmcnt(0)
	v_lshl_add_u64 v[12:13], v[12:13], 0, v[6:7]
	v_and_b32_e32 v6, 0xf8, v144
	v_lshl_add_u64 v[14:15], s[4:5], 0, v[6:7]
	v_lshl_add_u64 v[14:15], v[14:15], 0, s[2:3]
	s_mov_b32 s78, 0
	s_branch .LBB0_648

.Lgb4_poll:
	s_or_b64 exec, exec, s[0:1]
	v_mov_b32_e32 v32, 0x3308000
	global_load_dword v34, v32, s[44:45] offset:1024
	global_load_dwordx2 v[36:37], v32, s[44:45] offset:64
	global_load_dwordx2 v[38:39], v32, s[44:45] offset:96
	s_and_b64 exec, s[0:1], s[10:11]
	v_mov_b32_e32 v1, 0x3323000
	s_mov_b32 s77, 0

.Lgb4_other:
	s_or_b64 exec, exec, s[0:1]
	v_mov_b32_e32 v32, 0x3308000
	global_load_dword v34, v32, s[44:45] offset:1024
	global_load_dwordx2 v[36:37], v32, s[44:45] offset:64
	global_load_dwordx2 v[38:39], v32, s[44:45] offset:96
.LBB0_719:
	s_or_b64 exec, exec, s[0:1]
	s_waitcnt lgkmcnt(0)
	v_mov_b32_e32 v0, 0
	s_barrier
	v_mov_b32_e32 v178, s44
	v_mov_b32_e32 v179, s45
	s_add_u32 s60, s44, 0x3308040
	s_addc_u32 s61, s45, 0
	s_lshr_b32 s53, s84, 8
	s_bfe_u32 s55, s84, 0x20006
	s_cmpk_gt_u32 s84, 0xff
	s_cselect_b64 s[0:1], -1, 0
	s_waitcnt vmcnt(0)
	v_add_co_u32_e32 v0, vcc, 0x3308000, v178
	s_nop 1
	v_addc_co_u32_e32 v1, vcc, 0, v179, vcc
	v_mov_b32_e32 v0, v34
	v_mov_b32_e32 v1, 0x3308000
	v_mov_b32_e32 v180, v36
	v_mov_b32_e32 v181, v37
	v_mov_b32_e32 v182, v38
	v_mov_b32_e32 v183, v39
	s_waitcnt vmcnt(0) lgkmcnt(0)
	v_readfirstlane_b32 s2, v0
	v_cndmask_b32_e64 v0, 0, 1, s[0:1]
	v_cmp_ne_u32_e64 s[0:1], 1, v0
	s_cmp_eq_u32 s2, 0
	s_nop 0
	v_writelane_b32 v255, s0, 1
	s_nop 1
	v_writelane_b32 v255, s1, 2
	s_cbranch_scc1 .LBB0_723
	s_and_b64 vcc, exec, s[0:1]
	s_cbranch_vccz .LBB0_724
	s_cmpk_eq_i32 s46, 0x100
	s_mov_b64 s[0:1], -1
	s_cbranch_scc0 .LBB0_725

.Lgb9_poll:
	s_or_b64 exec, exec, s[0:1]
	v_mov_b32_e32 v32, 0x3308000
	global_load_dwordx2 v[34:35], v32, s[44:45] offset:168
	s_and_b64 exec, s[0:1], s[10:11]
	v_mov_b32_e32 v1, 0x3323000
	s_mov_b32 s77, 0

.Lgb9_other:
	s_or_b64 exec, exec, s[0:1]
	v_mov_b32_e32 v32, 0x3308000
	global_load_dwordx2 v[34:35], v32, s[44:45] offset:168
.LBB0_1357:
	s_or_b64 exec, exec, s[0:1]
	v_mov_b32_e32 v17, 0
	s_waitcnt lgkmcnt(0)
	s_barrier
	v_mov_b32_e32 v0, s44
	v_mov_b32_e32 v1, s45
	v_cndmask_b32_e64 v2, 0, 1, s[58:59]
	v_cmp_ne_u32_e64 s[0:1], 1, v2
	s_andn2_b64 vcc, exec, s[58:59]
	s_waitcnt vmcnt(0)
	v_readfirstlane_b32 s58, v0
	v_writelane_b32 v255, s0, 5
	v_readfirstlane_b32 s59, v1
	s_nop 0
	v_writelane_b32 v255, s1, 6
	s_cbranch_vccnz .LBB0_1360
	v_mov_b32_e32 v0, 0x3308000
	s_waitcnt vmcnt(0)
	v_mov_b32_e32 v0, v34
	v_mov_b32_e32 v1, v35
	s_add_u32 s66, s58, 0x3400000
	s_addc_u32 s67, s59, 0
	v_lshlrev_b32_e32 v16, 4, v176
	v_mbcnt_hi_u32_b32 v6, -1, v228
	s_add_u32 s89, s58, 0xb000000
	s_mov_b64 s[2:3], 0xd000000
	v_lshlrev_b32_e32 v4, 4, v173
	v_lshl_add_u64 v[2:3], s[58:59], 0, v[16:17]
	v_and_b32_e32 v7, 64, v6
	s_addc_u32 s90, s59, 0
	v_and_b32_e32 v131, 48, v4
	v_xor_b32_e32 v4, 4, v6
	v_lshl_add_u64 v[18:19], v[2:3], 0, s[2:3]
	v_add_u32_e32 v2, 64, v7
	s_add_u32 s91, s58, 0x1d000000
	v_lshlrev_b32_e32 v5, 17, v174
	v_lshlrev_b32_e32 v16, 5, v176
	v_cmp_lt_i32_e32 vcc, v4, v2
	s_addc_u32 s92, s59, 0
	s_lshl_b32 s2, s18, 6
	s_lshl_b32 s3, s85, 3
	v_cndmask_b32_e32 v2, v6, v4, vcc
	s_add_i32 s95, s2, s3
	s_mov_b64 s[6:7], 0x1b000000
	v_lshlrev_b32_e32 v132, 2, v2
	v_or_b32_e32 v2, s95, v174
	v_cmp_gt_u32_e64 s[0:1], 4, v176
	v_lshlrev_b32_e32 v128, 8, v176
	s_movk_i32 s53, 0x1600
	s_mov_b32 s55, 0xffff0000
	v_mov_b32_e32 v129, 0x358637bd
	s_mov_b32 s87, 0xf800000
	v_mov_b32_e32 v130, 0x260
	s_movk_i32 s88, 0x7fff
	s_lshl_b32 s93, s46, 6
	s_lshl_b32 s94, s46, 20
	v_lshlrev_b32_e32 v133, 14, v2
	s_mov_b32 s96, s52
	s_waitcnt vmcnt(0)
	v_lshl_add_u64 v[20:21], v[0:1], 0, v[16:17]
	v_and_b32_e32 v16, 0x60000, v5
	v_lshl_add_u64 v[0:1], s[58:59], 0, v[16:17]
	v_lshl_add_u64 v[22:23], v[0:1], 0, s[6:7]

.Lgb10_poll:
	s_or_b64 exec, exec, s[0:1]
	v_mov_b32_e32 v32, 0x3308000
	v_mov_b32_e32 v33, 0
	global_load_dwordx2 v[34:35], v32, s[44:45] offset:192
	global_load_dword v36, v32, s[44:45] offset:1024
	global_load_dwordx2 v[38:39], v33, s[60:61]
	s_and_b64 exec, s[0:1], s[10:11]
	v_mov_b32_e32 v1, 0x3323000
	s_mov_b32 s77, 0

.Lgb10_other:
	s_or_b64 exec, exec, s[0:1]
	v_mov_b32_e32 v32, 0x3308000
	v_mov_b32_e32 v33, 0
	global_load_dwordx2 v[34:35], v32, s[44:45] offset:192
	global_load_dword v36, v32, s[44:45] offset:1024
	global_load_dwordx2 v[38:39], v33, s[60:61]
.LBB0_1419:
	s_or_b64 exec, exec, s[0:1]
	v_mov_b32_e32 v2, 0x3308000
	s_waitcnt lgkmcnt(0)
	s_barrier
	v_mov_b32_e32 v4, 0
	s_waitcnt vmcnt(0)
	v_mov_b32_e32 v146, v34
	v_mov_b32_e32 v147, v35
	v_mov_b32_e32 v0, s44
	v_mov_b32_e32 v1, s45
	s_nop 0
	v_add_co_u32_e32 v2, vcc, 0x3308000, v0
	s_nop 1
	v_addc_co_u32_e32 v3, vcc, 0, v1, vcc
	v_mov_b32_e32 v5, v36
	v_mov_b32_e32 v144, v38
	v_mov_b32_e32 v145, v39
	v_readfirstlane_b32 s12, v0
	v_readfirstlane_b32 s13, v1
	s_waitcnt vmcnt(0) lgkmcnt(0)
	v_readfirstlane_b32 s0, v5
	s_cmp_eq_u32 s0, 0
	s_cbranch_scc1 .LBB0_1423
	v_readlane_b32 s0, v255, 1
	v_readlane_b32 s1, v255, 2
	s_and_b64 vcc, exec, s[0:1]
	s_cbranch_vccz .LBB0_1424
	s_cmpk_eq_i32 s46, 0x100
	s_mov_b64 s[0:1], -1
	s_cbranch_scc0 .LBB0_1425
